# seams: L1 invalidate issued after the arrival atomic returns (overlaps the leader's write-back / first poll) instead of before it
# baseline (speedup 1.0000x reference)
; __device__ __forceinline__ unsigned xb_add(unsigned* p, unsigned v) { return __hip_atomic_fetch_add(p, v, __ATOMIC_RELAXED, __HIP_MEMORY_SCOPE_AGENT); }
; __device__ __forceinline__ void xcd_barrier(const XcdBarrier& b) {
;     asm volatile("s_waitcnt vmcnt(0)" ::: "memory");
;     __syncthreads();
;     if (threadIdx.x == 0) {
;         unsigned* bar = b.bar;
;         __builtin_amdgcn_s_waitcnt(0);
;         unsigned nloc = b.st[0], nx = b.st[1];
;         if (nloc == 0u) { xcd_barrier_complete(bar, b.x, nloc, nx); b.st[0] = nloc; b.st[1] = nx; }
;         const unsigned old = xb_add(&bar[XB_XSUB(b.x)], 1u);
;         const unsigned gen = old / nloc;
;         if (old + 1u == (gen + 1u) * nloc) {
;             __builtin_amdgcn_fence(__ATOMIC_RELEASE, "agent");
;             asm volatile("s_waitcnt vmcnt(0)" ::: "memory");
;             const unsigned og = xb_add(&bar[XB_TOP], 1u);
.LBB0_144:
	s_cmp_lt_i32 s56, 2
	s_cselect_b64 s[10:11], -1, 0
	s_cmp_gt_i32 s57, 1
	s_cselect_b64 s[0:1], -1, 0
	s_and_b64 s[0:1], s[10:11], s[0:1]
	s_andn2_b64 vcc, exec, s[0:1]
	s_cbranch_vccnz .LBB0_443
	s_andn2_b64 vcc, exec, s[4:5]
	s_cbranch_vccnz .LBB0_199
	s_getreg_b32 s3, hwreg(HW_REG_XCC_ID, 0, 4)
	s_waitcnt vmcnt(0)
	v_cmp_eq_u32_e32 vcc, 0, v178
	s_waitcnt lgkmcnt(0)
	s_barrier
	s_and_saveexec_b64 s[0:1], vcc
	s_cbranch_execz .LBB0_198
	v_mov_b32_e32 v0, 0x23ff0
	ds_read2_b32 v[0:1], v0 offset1:1
	s_and_b32 s98, s3, 15
	s_lshl_b32 s98, s98, 8
	s_add_u32 s98, s54, s98
	s_addc_u32 s99, s55, 0
	s_add_u32 s98, s98, 0x22a3400
	s_addc_u32 s99, s99, 0
	v_mov_b32_e32 v2, 0
	v_mov_b32_e32 v3, 1
	global_atomic_add v4, v2, v3, s[98:99] sc0
	s_add_u32 s100, s54, 0x22a5400
	s_addc_u32 s101, s55, 0
	s_waitcnt vmcnt(0) lgkmcnt(0)
	v_mul_u32_u24_e32 v0, 1, v0
	v_mul_u32_u24_e32 v1, 1, v1
	v_add_u32_e32 v4, 1, v4
	v_cmp_eq_u32_e32 vcc, v4, v0
	buffer_inv sc1
	s_cbranch_vccz .Lxb_poll_s0
	buffer_wbl2 sc1
	s_waitcnt vmcnt(0)
	global_atomic_add v2, v3, s[100:101]

; __device__ __forceinline__ unsigned xb_add(unsigned* p, unsigned v) { return __hip_atomic_fetch_add(p, v, __ATOMIC_RELAXED, __HIP_MEMORY_SCOPE_AGENT); }
; __device__ __forceinline__ void xcd_barrier(const XcdBarrier& b) {
;     asm volatile("s_waitcnt vmcnt(0)" ::: "memory");
;     __syncthreads();
;     if (threadIdx.x == 0) {
;         unsigned* bar = b.bar;
;         __builtin_amdgcn_s_waitcnt(0);
;         unsigned nloc = b.st[0], nx = b.st[1];
;         if (nloc == 0u) { xcd_barrier_complete(bar, b.x, nloc, nx); b.st[0] = nloc; b.st[1] = nx; }
;         const unsigned old = xb_add(&bar[XB_XSUB(b.x)], 1u);
;         const unsigned gen = old / nloc;
;         if (old + 1u == (gen + 1u) * nloc) {
;             __builtin_amdgcn_fence(__ATOMIC_RELEASE, "agent");
;             asm volatile("s_waitcnt vmcnt(0)" ::: "memory");
;             const unsigned og = xb_add(&bar[XB_TOP], 1u);
.LBB0_443:
	s_cmp_lt_i32 s56, 3
	s_waitcnt lgkmcnt(0)
	s_cselect_b64 s[14:15], -1, 0
	s_cmp_gt_i32 s57, 2
	s_cselect_b64 s[0:1], -1, 0
	s_and_b64 s[0:1], s[14:15], s[0:1]
	s_andn2_b64 vcc, exec, s[0:1]
	s_cbranch_vccnz .LBB0_545
	s_and_b64 vcc, exec, s[10:11]
	s_cbranch_vccz .LBB0_498
	s_getreg_b32 s3, hwreg(HW_REG_XCC_ID, 0, 4)
	s_waitcnt vmcnt(0)
	v_cmp_eq_u32_e32 vcc, 0, v178
	s_waitcnt vmcnt(0)
	s_barrier
	s_and_saveexec_b64 s[0:1], vcc
	s_cbranch_execz .LBB0_497
	v_mov_b32_e32 v0, 0x23ff0
	ds_read2_b32 v[0:1], v0 offset1:1
	s_and_b32 s98, s3, 15
	s_lshl_b32 s98, s98, 8
	s_add_u32 s98, s54, s98
	s_addc_u32 s99, s55, 0
	s_add_u32 s98, s98, 0x22a3400
	s_addc_u32 s99, s99, 0
	v_mov_b32_e32 v2, 0
	v_mov_b32_e32 v3, 1
	global_atomic_add v4, v2, v3, s[98:99] sc0
	s_add_u32 s100, s54, 0x22a5400
	s_addc_u32 s101, s55, 0
	s_waitcnt vmcnt(0) lgkmcnt(0)
	v_mul_u32_u24_e32 v0, 2, v0
	v_mul_u32_u24_e32 v1, 2, v1
	v_add_u32_e32 v4, 1, v4
	v_cmp_eq_u32_e32 vcc, v4, v0
	buffer_inv sc1
	s_cbranch_vccz .Lxb_poll_s1
	buffer_wbl2 sc1
	s_waitcnt vmcnt(0)
	global_atomic_add v2, v3, s[100:101]

; __device__ __forceinline__ unsigned xb_add(unsigned* p, unsigned v) { return __hip_atomic_fetch_add(p, v, __ATOMIC_RELAXED, __HIP_MEMORY_SCOPE_AGENT); }
; __device__ __forceinline__ void xcd_barrier(const XcdBarrier& b) {
;     asm volatile("s_waitcnt vmcnt(0)" ::: "memory");
;     __syncthreads();
;     if (threadIdx.x == 0) {
;         unsigned* bar = b.bar;
;         __builtin_amdgcn_s_waitcnt(0);
;         unsigned nloc = b.st[0], nx = b.st[1];
;         if (nloc == 0u) { xcd_barrier_complete(bar, b.x, nloc, nx); b.st[0] = nloc; b.st[1] = nx; }
;         const unsigned old = xb_add(&bar[XB_XSUB(b.x)], 1u);
;         const unsigned gen = old / nloc;
;         if (old + 1u == (gen + 1u) * nloc) {
;             __builtin_amdgcn_fence(__ATOMIC_RELEASE, "agent");
;             asm volatile("s_waitcnt vmcnt(0)" ::: "memory");
;             const unsigned og = xb_add(&bar[XB_TOP], 1u);
.LBB0_545:
	s_cmp_lt_i32 s56, 4
	s_cselect_b64 s[0:1], -1, 0
	s_cmp_gt_i32 s57, 3
	s_cselect_b64 s[4:5], -1, 0
	s_and_b64 s[4:5], s[0:1], s[4:5]
	s_andn2_b64 vcc, exec, s[4:5]
	s_cbranch_vccnz .LBB0_670
	s_andn2_b64 vcc, exec, s[14:15]
	s_cbranch_vccnz .LBB0_558
	s_getreg_b32 s3, hwreg(HW_REG_XCC_ID, 0, 4)
	s_waitcnt vmcnt(0)
	v_cmp_eq_u32_e32 vcc, 0, v178
	s_waitcnt vmcnt(0)
	s_barrier
	s_and_saveexec_b64 s[4:5], vcc
	s_cbranch_execz .LBB0_631
	v_mov_b32_e32 v0, 0x23ff0
	ds_read2_b32 v[0:1], v0 offset1:1
	s_and_b32 s98, s3, 15
	s_lshl_b32 s98, s98, 8
	s_add_u32 s98, s54, s98
	s_addc_u32 s99, s55, 0
	s_add_u32 s98, s98, 0x22a3400
	s_addc_u32 s99, s99, 0
	v_mov_b32_e32 v2, 0
	v_mov_b32_e32 v3, 1
	global_atomic_add v4, v2, v3, s[98:99] sc0
	s_add_u32 s100, s54, 0x22a5400
	s_addc_u32 s101, s55, 0
	s_waitcnt vmcnt(0) lgkmcnt(0)
	v_mul_u32_u24_e32 v0, 3, v0
	v_mul_u32_u24_e32 v1, 3, v1
	v_add_u32_e32 v4, 1, v4
	v_cmp_eq_u32_e32 vcc, v4, v0
	buffer_inv sc1
	s_cbranch_vccz .Lxb_poll_s2
	buffer_wbl2 sc1
	s_waitcnt vmcnt(0)
	global_atomic_add v2, v3, s[100:101]

; __device__ __forceinline__ unsigned xb_add(unsigned* p, unsigned v) { return __hip_atomic_fetch_add(p, v, __ATOMIC_RELAXED, __HIP_MEMORY_SCOPE_AGENT); }
; __device__ __forceinline__ void xcd_barrier(const XcdBarrier& b) {
;     asm volatile("s_waitcnt vmcnt(0)" ::: "memory");
;     __syncthreads();
;     if (threadIdx.x == 0) {
;         unsigned* bar = b.bar;
;         __builtin_amdgcn_s_waitcnt(0);
;         unsigned nloc = b.st[0], nx = b.st[1];
;         if (nloc == 0u) { xcd_barrier_complete(bar, b.x, nloc, nx); b.st[0] = nloc; b.st[1] = nx; }
;         const unsigned old = xb_add(&bar[XB_XSUB(b.x)], 1u);
;         const unsigned gen = old / nloc;
;         if (old + 1u == (gen + 1u) * nloc) {
;             __builtin_amdgcn_fence(__ATOMIC_RELEASE, "agent");
;             asm volatile("s_waitcnt vmcnt(0)" ::: "memory");
;             const unsigned og = xb_add(&bar[XB_TOP], 1u);
.LBB0_670:
	s_cmp_lt_i32 s56, 5
	s_cselect_b64 s[14:15], -1, 0
	s_cmp_gt_i32 s57, 4
	s_cselect_b64 s[4:5], -1, 0
	s_and_b64 s[4:5], s[14:15], s[4:5]
	s_andn2_b64 vcc, exec, s[4:5]
	s_cbranch_vccnz .LBB0_745
	s_andn2_b64 vcc, exec, s[0:1]
	s_cbranch_vccnz .LBB0_725
	s_getreg_b32 s3, hwreg(HW_REG_XCC_ID, 0, 4)
	s_waitcnt vmcnt(0)
	v_cmp_eq_u32_e32 vcc, 0, v178
	s_waitcnt vmcnt(0)
	s_barrier
	s_and_saveexec_b64 s[0:1], vcc
	s_cbranch_execz .LBB0_724
	v_mov_b32_e32 v0, 0x23ff0
	ds_read2_b32 v[0:1], v0 offset1:1
	s_and_b32 s98, s3, 15
	s_lshl_b32 s98, s98, 8
	s_add_u32 s98, s54, s98
	s_addc_u32 s99, s55, 0
	s_add_u32 s98, s98, 0x22a3400
	s_addc_u32 s99, s99, 0
	v_mov_b32_e32 v2, 0
	v_mov_b32_e32 v3, 1
	global_atomic_add v4, v2, v3, s[98:99] sc0
	s_add_u32 s100, s54, 0x22a5400
	s_addc_u32 s101, s55, 0
	s_waitcnt vmcnt(0) lgkmcnt(0)
	v_mul_u32_u24_e32 v0, 4, v0
	v_mul_u32_u24_e32 v1, 4, v1
	v_add_u32_e32 v4, 1, v4
	v_cmp_eq_u32_e32 vcc, v4, v0
	buffer_inv sc1
	s_cbranch_vccz .Lxb_poll_s3
	buffer_wbl2 sc1
	s_waitcnt vmcnt(0)
	global_atomic_add v2, v3, s[100:101]

; __device__ __forceinline__ unsigned xb_add(unsigned* p, unsigned v) { return __hip_atomic_fetch_add(p, v, __ATOMIC_RELAXED, __HIP_MEMORY_SCOPE_AGENT); }
; __device__ __forceinline__ void xcd_barrier(const XcdBarrier& b) {
;     asm volatile("s_waitcnt vmcnt(0)" ::: "memory");
;     __syncthreads();
;     if (threadIdx.x == 0) {
;         unsigned* bar = b.bar;
;         __builtin_amdgcn_s_waitcnt(0);
;         unsigned nloc = b.st[0], nx = b.st[1];
;         if (nloc == 0u) { xcd_barrier_complete(bar, b.x, nloc, nx); b.st[0] = nloc; b.st[1] = nx; }
;         const unsigned old = xb_add(&bar[XB_XSUB(b.x)], 1u);
;         const unsigned gen = old / nloc;
;         if (old + 1u == (gen + 1u) * nloc) {
;             __builtin_amdgcn_fence(__ATOMIC_RELEASE, "agent");
;             asm volatile("s_waitcnt vmcnt(0)" ::: "memory");
;             const unsigned og = xb_add(&bar[XB_TOP], 1u);
.LBB0_745:
	s_cmp_lt_i32 s56, 6
	s_cselect_b64 s[0:1], -1, 0
	s_cmp_gt_i32 s57, 5
	s_cselect_b64 s[4:5], -1, 0
	s_and_b64 s[0:1], s[0:1], s[4:5]
	s_andn2_b64 vcc, exec, s[0:1]
	s_cbranch_vccnz .LBB0_841
	s_andn2_b64 vcc, exec, s[14:15]
	s_cbranch_vccnz .LBB0_800
	s_getreg_b32 s3, hwreg(HW_REG_XCC_ID, 0, 4)
	s_waitcnt vmcnt(0)
	v_cmp_eq_u32_e32 vcc, 0, v178
	s_waitcnt vmcnt(0)
	s_barrier
	s_and_saveexec_b64 s[0:1], vcc
	s_cbranch_execz .LBB0_799
	v_mov_b32_e32 v0, 0x23ff0
	ds_read2_b32 v[0:1], v0 offset1:1
	s_and_b32 s98, s3, 15
	s_lshl_b32 s98, s98, 8
	s_add_u32 s98, s54, s98
	s_addc_u32 s99, s55, 0
	s_add_u32 s98, s98, 0x22a3400
	s_addc_u32 s99, s99, 0
	v_mov_b32_e32 v2, 0
	v_mov_b32_e32 v3, 1
	global_atomic_add v4, v2, v3, s[98:99] sc0
	s_add_u32 s100, s54, 0x22a5400
	s_addc_u32 s101, s55, 0
	s_waitcnt vmcnt(0) lgkmcnt(0)
	v_mul_u32_u24_e32 v0, 5, v0
	v_mul_u32_u24_e32 v1, 5, v1
	v_add_u32_e32 v4, 1, v4
	v_cmp_eq_u32_e32 vcc, v4, v0
	buffer_inv sc1
	s_cbranch_vccz .Lxb_poll_s4
	buffer_wbl2 sc1
	s_waitcnt vmcnt(0)
	global_atomic_add v2, v3, s[100:101]

; __device__ __forceinline__ unsigned xb_add(unsigned* p, unsigned v) { return __hip_atomic_fetch_add(p, v, __ATOMIC_RELAXED, __HIP_MEMORY_SCOPE_AGENT); }
; __device__ __forceinline__ void xcd_barrier(const XcdBarrier& b) {
;     asm volatile("s_waitcnt vmcnt(0)" ::: "memory");
;     __syncthreads();
;     if (threadIdx.x == 0) {
;         unsigned* bar = b.bar;
;         __builtin_amdgcn_s_waitcnt(0);
;         unsigned nloc = b.st[0], nx = b.st[1];
;         if (nloc == 0u) { xcd_barrier_complete(bar, b.x, nloc, nx); b.st[0] = nloc; b.st[1] = nx; }
;         const unsigned old = xb_add(&bar[XB_XSUB(b.x)], 1u);
;         const unsigned gen = old / nloc;
;         if (old + 1u == (gen + 1u) * nloc) {
;             __builtin_amdgcn_fence(__ATOMIC_RELEASE, "agent");
;             asm volatile("s_waitcnt vmcnt(0)" ::: "memory");
;             const unsigned og = xb_add(&bar[XB_TOP], 1u);
.LBB0_841:
	s_cmp_lt_i32 s56, 8
	s_cselect_b64 s[6:7], -1, 0
	s_cmp_gt_i32 s57, 7
	s_cselect_b64 s[0:1], -1, 0
	s_and_b64 s[0:1], s[6:7], s[0:1]
	s_andn2_b64 vcc, exec, s[0:1]
	s_cbranch_vccnz .LBB0_934
	s_cmp_gt_i32 s56, 6
	s_cbranch_scc1 .LBB0_896
	s_getreg_b32 s3, hwreg(HW_REG_XCC_ID, 0, 4)
	s_waitcnt vmcnt(0)
	v_cmp_eq_u32_e32 vcc, 0, v178
	s_waitcnt vmcnt(0)
	s_barrier
	s_and_saveexec_b64 s[0:1], vcc
	s_cbranch_execz .LBB0_895
	v_mov_b32_e32 v0, 0x23ff0
	ds_read2_b32 v[0:1], v0 offset1:1
	s_and_b32 s98, s3, 15
	s_lshl_b32 s98, s98, 8
	s_add_u32 s98, s54, s98
	s_addc_u32 s99, s55, 0
	s_add_u32 s98, s98, 0x22a3400
	s_addc_u32 s99, s99, 0
	v_mov_b32_e32 v2, 0
	v_mov_b32_e32 v3, 1
	global_atomic_add v4, v2, v3, s[98:99] sc0
	s_add_u32 s100, s54, 0x22a5400
	s_addc_u32 s101, s55, 0
	s_waitcnt vmcnt(0) lgkmcnt(0)
	v_mul_u32_u24_e32 v0, 6, v0
	v_mul_u32_u24_e32 v1, 6, v1
	v_add_u32_e32 v4, 1, v4
	v_cmp_eq_u32_e32 vcc, v4, v0
	buffer_inv sc1
	s_cbranch_vccz .Lxb_poll_s5
	buffer_wbl2 sc1
	s_waitcnt vmcnt(0)
	global_atomic_add v2, v3, s[100:101]

; __device__ __forceinline__ unsigned xb_add(unsigned* p, unsigned v) { return __hip_atomic_fetch_add(p, v, __ATOMIC_RELAXED, __HIP_MEMORY_SCOPE_AGENT); }
; __device__ __forceinline__ void xcd_barrier(const XcdBarrier& b) {
;     asm volatile("s_waitcnt vmcnt(0)" ::: "memory");
;     __syncthreads();
;     if (threadIdx.x == 0) {
;         unsigned* bar = b.bar;
;         __builtin_amdgcn_s_waitcnt(0);
;         unsigned nloc = b.st[0], nx = b.st[1];
;         if (nloc == 0u) { xcd_barrier_complete(bar, b.x, nloc, nx); b.st[0] = nloc; b.st[1] = nx; }
;         const unsigned old = xb_add(&bar[XB_XSUB(b.x)], 1u);
;         const unsigned gen = old / nloc;
;         if (old + 1u == (gen + 1u) * nloc) {
;             __builtin_amdgcn_fence(__ATOMIC_RELEASE, "agent");
;             asm volatile("s_waitcnt vmcnt(0)" ::: "memory");
;             const unsigned og = xb_add(&bar[XB_TOP], 1u);
.LBB0_934:
	s_cmp_lt_i32 s56, 9
	s_cselect_b64 s[4:5], -1, 0
	s_cmp_gt_i32 s57, 8
	s_cselect_b64 s[0:1], -1, 0
	s_and_b64 s[0:1], s[4:5], s[0:1]
	s_andn2_b64 vcc, exec, s[0:1]
	s_cbranch_vccnz .LBB0_1079
	s_andn2_b64 vcc, exec, s[6:7]
	s_cbranch_vccnz .LBB0_989
	s_getreg_b32 s3, hwreg(HW_REG_XCC_ID, 0, 4)
	s_waitcnt vmcnt(0)
	v_cmp_eq_u32_e32 vcc, 0, v178
	s_waitcnt vmcnt(0) lgkmcnt(0)
	s_barrier
	s_and_saveexec_b64 s[0:1], vcc
	s_cbranch_execz .LBB0_988
	v_mov_b32_e32 v0, 0x23ff0
	ds_read2_b32 v[0:1], v0 offset1:1
	s_and_b32 s98, s3, 15
	s_lshl_b32 s98, s98, 8
	s_add_u32 s98, s54, s98
	s_addc_u32 s99, s55, 0
	s_add_u32 s98, s98, 0x22a3400
	s_addc_u32 s99, s99, 0
	v_mov_b32_e32 v2, 0
	v_mov_b32_e32 v3, 1
	global_atomic_add v4, v2, v3, s[98:99] sc0
	s_add_u32 s100, s54, 0x22a5400
	s_addc_u32 s101, s55, 0
	s_waitcnt vmcnt(0) lgkmcnt(0)
	v_mul_u32_u24_e32 v0, 7, v0
	v_mul_u32_u24_e32 v1, 7, v1
	v_add_u32_e32 v4, 1, v4
	v_cmp_eq_u32_e32 vcc, v4, v0
	buffer_inv sc1
	s_cbranch_vccz .Lxb_poll_s6
	buffer_wbl2 sc1
	s_waitcnt vmcnt(0)
	global_atomic_add v2, v3, s[100:101]

; __device__ __forceinline__ unsigned xb_add(unsigned* p, unsigned v) { return __hip_atomic_fetch_add(p, v, __ATOMIC_RELAXED, __HIP_MEMORY_SCOPE_AGENT); }
; __device__ __forceinline__ void xcd_barrier(const XcdBarrier& b) {
;     asm volatile("s_waitcnt vmcnt(0)" ::: "memory");
;     __syncthreads();
;     if (threadIdx.x == 0) {
;         unsigned* bar = b.bar;
;         __builtin_amdgcn_s_waitcnt(0);
;         unsigned nloc = b.st[0], nx = b.st[1];
;         if (nloc == 0u) { xcd_barrier_complete(bar, b.x, nloc, nx); b.st[0] = nloc; b.st[1] = nx; }
;         const unsigned old = xb_add(&bar[XB_XSUB(b.x)], 1u);
;         const unsigned gen = old / nloc;
;         if (old + 1u == (gen + 1u) * nloc) {
;             __builtin_amdgcn_fence(__ATOMIC_RELEASE, "agent");
;             asm volatile("s_waitcnt vmcnt(0)" ::: "memory");
;             const unsigned og = xb_add(&bar[XB_TOP], 1u);
.LBB0_1079:
	s_cmp_lt_i32 s56, 10
	s_cselect_b64 s[6:7], -1, 0
	s_cmp_gt_i32 s57, 9
	s_cselect_b64 s[0:1], -1, 0
	s_and_b64 s[0:1], s[6:7], s[0:1]
	s_andn2_b64 vcc, exec, s[0:1]
	s_cbranch_vccnz .LBB0_1139
	s_andn2_b64 vcc, exec, s[4:5]
	s_cbranch_vccnz .LBB0_1134
	s_getreg_b32 s3, hwreg(HW_REG_XCC_ID, 0, 4)
	s_waitcnt vmcnt(0)
	v_cmp_eq_u32_e32 vcc, 0, v178
	s_waitcnt vmcnt(0) lgkmcnt(0)
	s_barrier
	s_and_saveexec_b64 s[0:1], vcc
	s_cbranch_execz .LBB0_1133
	v_mov_b32_e32 v0, 0x23ff0
	ds_read2_b32 v[0:1], v0 offset1:1
	s_and_b32 s98, s3, 15
	s_lshl_b32 s98, s98, 8
	s_add_u32 s98, s54, s98
	s_addc_u32 s99, s55, 0
	s_add_u32 s98, s98, 0x22a3400
	s_addc_u32 s99, s99, 0
	v_mov_b32_e32 v2, 0
	v_mov_b32_e32 v3, 1
	global_atomic_add v4, v2, v3, s[98:99] sc0
	s_add_u32 s100, s54, 0x22a5400
	s_addc_u32 s101, s55, 0
	s_waitcnt vmcnt(0) lgkmcnt(0)
	v_mul_u32_u24_e32 v0, 8, v0
	v_mul_u32_u24_e32 v1, 8, v1
	v_add_u32_e32 v4, 1, v4
	v_cmp_eq_u32_e32 vcc, v4, v0
	buffer_inv sc1
	s_cbranch_vccz .Lxb_poll_s7
	buffer_wbl2 sc1
	s_waitcnt vmcnt(0)
	global_atomic_add v2, v3, s[100:101]

; __device__ __forceinline__ unsigned xb_add(unsigned* p, unsigned v) { return __hip_atomic_fetch_add(p, v, __ATOMIC_RELAXED, __HIP_MEMORY_SCOPE_AGENT); }
; __device__ __forceinline__ void xcd_barrier(const XcdBarrier& b) {
;     asm volatile("s_waitcnt vmcnt(0)" ::: "memory");
;     __syncthreads();
;     if (threadIdx.x == 0) {
;         unsigned* bar = b.bar;
;         __builtin_amdgcn_s_waitcnt(0);
;         unsigned nloc = b.st[0], nx = b.st[1];
;         if (nloc == 0u) { xcd_barrier_complete(bar, b.x, nloc, nx); b.st[0] = nloc; b.st[1] = nx; }
;         const unsigned old = xb_add(&bar[XB_XSUB(b.x)], 1u);
;         const unsigned gen = old / nloc;
;         if (old + 1u == (gen + 1u) * nloc) {
;             __builtin_amdgcn_fence(__ATOMIC_RELEASE, "agent");
;             asm volatile("s_waitcnt vmcnt(0)" ::: "memory");
;             const unsigned og = xb_add(&bar[XB_TOP], 1u);
.LBB0_1139:
	s_cmp_lt_i32 s56, 11
	s_cselect_b64 s[4:5], -1, 0
	s_cmp_gt_i32 s57, 10
	s_cselect_b64 s[0:1], -1, 0
	s_and_b64 s[0:1], s[4:5], s[0:1]
	s_andn2_b64 vcc, exec, s[0:1]
	s_cbranch_vccnz .LBB0_1210
	s_andn2_b64 vcc, exec, s[6:7]
	s_cbranch_vccnz .LBB0_1194
	s_getreg_b32 s3, hwreg(HW_REG_XCC_ID, 0, 4)
	s_waitcnt vmcnt(0)
	v_cmp_eq_u32_e32 vcc, 0, v178
	s_waitcnt vmcnt(0) lgkmcnt(0)
	s_barrier
	s_and_saveexec_b64 s[0:1], vcc
	s_cbranch_execz .LBB0_1193
	v_mov_b32_e32 v0, 0x23ff0
	ds_read2_b32 v[0:1], v0 offset1:1
	s_and_b32 s98, s3, 15
	s_lshl_b32 s98, s98, 8
	s_add_u32 s98, s54, s98
	s_addc_u32 s99, s55, 0
	s_add_u32 s98, s98, 0x22a3400
	s_addc_u32 s99, s99, 0
	v_mov_b32_e32 v2, 0
	v_mov_b32_e32 v3, 1
	global_atomic_add v4, v2, v3, s[98:99] sc0
	s_add_u32 s100, s54, 0x22a5400
	s_addc_u32 s101, s55, 0
	s_waitcnt vmcnt(0) lgkmcnt(0)
	v_mul_u32_u24_e32 v0, 9, v0
	v_mul_u32_u24_e32 v1, 9, v1
	v_add_u32_e32 v4, 1, v4
	v_cmp_eq_u32_e32 vcc, v4, v0
	buffer_inv sc1
	s_cbranch_vccz .Lxb_poll_s8
	buffer_wbl2 sc1
	s_waitcnt vmcnt(0)
	global_atomic_add v2, v3, s[100:101]

; __device__ __forceinline__ unsigned xb_add(unsigned* p, unsigned v) { return __hip_atomic_fetch_add(p, v, __ATOMIC_RELAXED, __HIP_MEMORY_SCOPE_AGENT); }
; __device__ __forceinline__ void xcd_barrier(const XcdBarrier& b) {
;     asm volatile("s_waitcnt vmcnt(0)" ::: "memory");
;     __syncthreads();
;     if (threadIdx.x == 0) {
;         unsigned* bar = b.bar;
;         __builtin_amdgcn_s_waitcnt(0);
;         unsigned nloc = b.st[0], nx = b.st[1];
;         if (nloc == 0u) { xcd_barrier_complete(bar, b.x, nloc, nx); b.st[0] = nloc; b.st[1] = nx; }
;         const unsigned old = xb_add(&bar[XB_XSUB(b.x)], 1u);
;         const unsigned gen = old / nloc;
;         if (old + 1u == (gen + 1u) * nloc) {
;             __builtin_amdgcn_fence(__ATOMIC_RELEASE, "agent");
;             asm volatile("s_waitcnt vmcnt(0)" ::: "memory");
;             const unsigned og = xb_add(&bar[XB_TOP], 1u);
.LBB0_1210:
	s_cmp_lt_i32 s56, 12
	s_cselect_b64 s[10:11], -1, 0
	s_cmp_gt_i32 s57, 11
	s_cselect_b64 s[0:1], -1, 0
	s_and_b64 s[0:1], s[10:11], s[0:1]
	s_andn2_b64 vcc, exec, s[0:1]
	s_cbranch_vccnz .LBB0_1307
	s_andn2_b64 vcc, exec, s[4:5]
	s_cbranch_vccnz .LBB0_1265
	s_getreg_b32 s3, hwreg(HW_REG_XCC_ID, 0, 4)
	s_waitcnt vmcnt(0)
	v_cmp_eq_u32_e32 vcc, 0, v178
	s_waitcnt vmcnt(0) lgkmcnt(0)
	s_barrier
	s_and_saveexec_b64 s[0:1], vcc
	s_cbranch_execz .LBB0_1264
	v_mov_b32_e32 v0, 0x23ff0
	ds_read2_b32 v[0:1], v0 offset1:1
	s_and_b32 s98, s3, 15
	s_lshl_b32 s98, s98, 8
	s_add_u32 s98, s54, s98
	s_addc_u32 s99, s55, 0
	s_add_u32 s98, s98, 0x22a3400
	s_addc_u32 s99, s99, 0
	v_mov_b32_e32 v2, 0
	v_mov_b32_e32 v3, 1
	global_atomic_add v4, v2, v3, s[98:99] sc0
	s_add_u32 s100, s54, 0x22a5400
	s_addc_u32 s101, s55, 0
	s_waitcnt vmcnt(0) lgkmcnt(0)
	v_mul_u32_u24_e32 v0, 10, v0
	v_mul_u32_u24_e32 v1, 10, v1
	v_add_u32_e32 v4, 1, v4
	v_cmp_eq_u32_e32 vcc, v4, v0
	buffer_inv sc1
	s_cbranch_vccz .Lxb_poll_s9
	buffer_wbl2 sc1
	s_waitcnt vmcnt(0)
	global_atomic_add v2, v3, s[100:101]

; __device__ __forceinline__ unsigned xb_add(unsigned* p, unsigned v) { return __hip_atomic_fetch_add(p, v, __ATOMIC_RELAXED, __HIP_MEMORY_SCOPE_AGENT); }
; __device__ __forceinline__ void xcd_barrier(const XcdBarrier& b) {
;     asm volatile("s_waitcnt vmcnt(0)" ::: "memory");
;     __syncthreads();
;     if (threadIdx.x == 0) {
;         unsigned* bar = b.bar;
;         __builtin_amdgcn_s_waitcnt(0);
;         unsigned nloc = b.st[0], nx = b.st[1];
;         if (nloc == 0u) { xcd_barrier_complete(bar, b.x, nloc, nx); b.st[0] = nloc; b.st[1] = nx; }
;         const unsigned old = xb_add(&bar[XB_XSUB(b.x)], 1u);
;         const unsigned gen = old / nloc;
;         if (old + 1u == (gen + 1u) * nloc) {
;             __builtin_amdgcn_fence(__ATOMIC_RELEASE, "agent");
;             asm volatile("s_waitcnt vmcnt(0)" ::: "memory");
;             const unsigned og = xb_add(&bar[XB_TOP], 1u);
.LBB0_1307:
	s_cmp_lt_i32 s56, 13
	s_cselect_b64 s[6:7], -1, 0
	s_cmp_gt_i32 s57, 12
	s_cselect_b64 s[0:1], -1, 0
	s_and_b64 s[0:1], s[6:7], s[0:1]
	s_andn2_b64 vcc, exec, s[0:1]
	s_cbranch_vccnz .LBB0_1460
	s_andn2_b64 vcc, exec, s[10:11]
	s_cbranch_vccnz .LBB0_1362
	s_getreg_b32 s3, hwreg(HW_REG_XCC_ID, 0, 4)
	s_waitcnt vmcnt(0)
	v_cmp_eq_u32_e32 vcc, 0, v178
	s_waitcnt vmcnt(0) lgkmcnt(0)
	s_barrier
	s_and_saveexec_b64 s[0:1], vcc
	s_cbranch_execz .LBB0_1361
	v_mov_b32_e32 v0, 0x23ff0
	ds_read2_b32 v[0:1], v0 offset1:1
	s_and_b32 s98, s3, 15
	s_lshl_b32 s98, s98, 8
	s_add_u32 s98, s54, s98
	s_addc_u32 s99, s55, 0
	s_add_u32 s98, s98, 0x22a3400
	s_addc_u32 s99, s99, 0
	v_mov_b32_e32 v2, 0
	v_mov_b32_e32 v3, 1
	global_atomic_add v4, v2, v3, s[98:99] sc0
	s_add_u32 s100, s54, 0x22a5400
	s_addc_u32 s101, s55, 0
	s_waitcnt vmcnt(0) lgkmcnt(0)
	v_mul_u32_u24_e32 v0, 11, v0
	v_mul_u32_u24_e32 v1, 11, v1
	v_add_u32_e32 v4, 1, v4
	v_cmp_eq_u32_e32 vcc, v4, v0
	buffer_inv sc1
	s_cbranch_vccz .Lxb_poll_s10
	buffer_wbl2 sc1
	s_waitcnt vmcnt(0)
	global_atomic_add v2, v3, s[100:101]

; __device__ __forceinline__ unsigned xb_add(unsigned* p, unsigned v) { return __hip_atomic_fetch_add(p, v, __ATOMIC_RELAXED, __HIP_MEMORY_SCOPE_AGENT); }
; __device__ __forceinline__ void xcd_barrier(const XcdBarrier& b) {
;     asm volatile("s_waitcnt vmcnt(0)" ::: "memory");
;     __syncthreads();
;     if (threadIdx.x == 0) {
;         unsigned* bar = b.bar;
;         __builtin_amdgcn_s_waitcnt(0);
;         unsigned nloc = b.st[0], nx = b.st[1];
;         if (nloc == 0u) { xcd_barrier_complete(bar, b.x, nloc, nx); b.st[0] = nloc; b.st[1] = nx; }
;         const unsigned old = xb_add(&bar[XB_XSUB(b.x)], 1u);
;         const unsigned gen = old / nloc;
;         if (old + 1u == (gen + 1u) * nloc) {
;             __builtin_amdgcn_fence(__ATOMIC_RELEASE, "agent");
;             asm volatile("s_waitcnt vmcnt(0)" ::: "memory");
;             const unsigned og = xb_add(&bar[XB_TOP], 1u);
.Lsk_nowb:
.LBB0_1460:
	s_cmp_lt_i32 s56, 14
	s_cselect_b64 s[0:1], -1, 0
	s_cmp_gt_i32 s57, 13
	s_cselect_b64 s[4:5], -1, 0
	s_and_b64 s[0:1], s[0:1], s[4:5]
	s_andn2_b64 vcc, exec, s[0:1]
	s_cbranch_vccnz .LBB0_1520
	s_andn2_b64 vcc, exec, s[6:7]
	s_cbranch_vccnz .LBB0_1515
	s_getreg_b32 s3, hwreg(HW_REG_XCC_ID, 0, 4)
	s_waitcnt vmcnt(0)
	v_cmp_eq_u32_e32 vcc, 0, v178
	s_waitcnt vmcnt(0) lgkmcnt(0)
	s_barrier
	s_and_saveexec_b64 s[0:1], vcc
	s_cbranch_execz .LBB0_1514
	v_mov_b32_e32 v0, 0x23ff0
	ds_read2_b32 v[0:1], v0 offset1:1
	s_and_b32 s98, s3, 15
	s_lshl_b32 s98, s98, 8
	s_add_u32 s98, s54, s98
	s_addc_u32 s99, s55, 0
	s_add_u32 s98, s98, 0x22a3400
	s_addc_u32 s99, s99, 0
	v_mov_b32_e32 v2, 0
	v_mov_b32_e32 v3, 1
	global_atomic_add v4, v2, v3, s[98:99] sc0
	s_add_u32 s100, s54, 0x22a5400
	s_addc_u32 s101, s55, 0
	s_waitcnt vmcnt(0) lgkmcnt(0)
	v_mul_u32_u24_e32 v0, 12, v0
	v_mul_u32_u24_e32 v1, 12, v1
	v_add_u32_e32 v4, 1, v4
	v_cmp_eq_u32_e32 vcc, v4, v0
	buffer_inv sc1
	s_cbranch_vccz .Lxb_poll_s11
	buffer_wbl2 sc1
	s_waitcnt vmcnt(0)
	global_atomic_add v2, v3, s[100:101]
